# v33 plus the same LDS fragment-read pipelining in the odin and evin plain-unit (128x128) K loops
# baseline (speedup 1.0000x reference)
.LBB0_517:
	s_addk_i32 s28, 0x80
	s_setprio 1
	ds_read_b128 v[164:167], v154
	ds_read_b128 v[168:171], v156 offset:16384
	ds_read_b128 v[172:175], v156 offset:20480
	s_waitcnt lgkmcnt(1)
	v_mfma_f32_32x32x16_bf16 v[52:67], v[164:167], v[168:171], v[52:67]
	ds_read_b128 v[176:179], v154 offset:4096
	s_waitcnt lgkmcnt(1)
	v_mfma_f32_32x32x16_bf16 v[36:51], v[164:167], v[172:175], v[36:51]
	ds_read_b128 v[180:183], v157
	ds_read_b128 v[184:187], v158 offset:16384
	s_waitcnt lgkmcnt(2)
	v_mfma_f32_32x32x16_bf16 v[20:35], v[176:179], v[168:171], v[20:35]
	ds_read_b128 v[188:191], v158 offset:20480
	v_mfma_f32_32x32x16_bf16 v[4:19], v[176:179], v[172:175], v[4:19]
	s_waitcnt lgkmcnt(1)
	v_mfma_f32_32x32x16_bf16 v[52:67], v[180:183], v[184:187], v[52:67]
	ds_read_b128 v[164:167], v157 offset:4096
	s_waitcnt lgkmcnt(1)
	v_mfma_f32_32x32x16_bf16 v[36:51], v[180:183], v[188:191], v[36:51]
	ds_read_b128 v[176:179], v159
	ds_read_b128 v[168:171], v160 offset:16384
	s_waitcnt lgkmcnt(2)
	v_mfma_f32_32x32x16_bf16 v[20:35], v[164:167], v[184:187], v[20:35]
	ds_read_b128 v[172:175], v160 offset:20480
	v_mfma_f32_32x32x16_bf16 v[4:19], v[164:167], v[188:191], v[4:19]
	s_waitcnt lgkmcnt(1)
	v_mfma_f32_32x32x16_bf16 v[52:67], v[176:179], v[168:171], v[52:67]
	ds_read_b128 v[180:183], v159 offset:4096
	s_waitcnt lgkmcnt(1)
	v_mfma_f32_32x32x16_bf16 v[36:51], v[176:179], v[172:175], v[36:51]
	ds_read_b128 v[164:167], v161
	ds_read_b128 v[184:187], v162 offset:16384
	s_waitcnt lgkmcnt(2)
	v_mfma_f32_32x32x16_bf16 v[20:35], v[180:183], v[168:171], v[20:35]
	ds_read_b128 v[188:191], v162 offset:20480
	v_mfma_f32_32x32x16_bf16 v[4:19], v[180:183], v[172:175], v[4:19]
	s_waitcnt lgkmcnt(1)
	v_mfma_f32_32x32x16_bf16 v[52:67], v[164:167], v[184:187], v[52:67]
	ds_read_b128 v[176:179], v161 offset:4096
	s_waitcnt lgkmcnt(1)
	v_mfma_f32_32x32x16_bf16 v[36:51], v[164:167], v[188:191], v[36:51]
	s_waitcnt lgkmcnt(0)
	v_mfma_f32_32x32x16_bf16 v[20:35], v[176:179], v[184:187], v[20:35]
	v_mfma_f32_32x32x16_bf16 v[4:19], v[176:179], v[188:191], v[4:19]
	s_setprio 0
	v_lshl_add_u64 v[134:135], v[134:135], 0, s[82:83]
	v_lshl_add_u64 v[136:137], v[136:137], 0, s[82:83]
	v_lshl_add_u64 v[138:139], v[138:139], 0, s[82:83]
	v_lshl_add_u64 v[140:141], v[140:141], 0, s[82:83]
	v_lshl_add_u64 v[142:143], v[142:143], 0, s[82:83]
	v_lshl_add_u64 v[144:145], v[144:145], 0, s[82:83]
	v_lshl_add_u64 v[146:147], v[146:147], 0, s[82:83]
	s_andn2_b64 vcc, exec, s[2:3]
	v_lshl_add_u64 v[148:149], v[148:149], 0, s[82:83]
	s_barrier
	s_cbranch_vccz .LBB0_537

.LBB0_528:
	s_setprio 1
	ds_read_b128 v[164:167], v154
	ds_read_b128 v[168:171], v156 offset:16384
	ds_read_b128 v[172:175], v156 offset:20480
	s_waitcnt lgkmcnt(1)
	v_mfma_f32_32x32x16_bf16 v[52:67], v[164:167], v[168:171], v[52:67]
	ds_read_b128 v[176:179], v154 offset:4096
	s_waitcnt lgkmcnt(1)
	v_mfma_f32_32x32x16_bf16 v[36:51], v[164:167], v[172:175], v[36:51]
	ds_read_b128 v[180:183], v157
	ds_read_b128 v[184:187], v158 offset:16384
	s_waitcnt lgkmcnt(2)
	v_mfma_f32_32x32x16_bf16 v[20:35], v[176:179], v[168:171], v[20:35]
	ds_read_b128 v[188:191], v158 offset:20480
	v_mfma_f32_32x32x16_bf16 v[4:19], v[176:179], v[172:175], v[4:19]
	s_waitcnt lgkmcnt(1)
	v_mfma_f32_32x32x16_bf16 v[52:67], v[180:183], v[184:187], v[52:67]
	ds_read_b128 v[164:167], v157 offset:4096
	s_waitcnt lgkmcnt(1)
	v_mfma_f32_32x32x16_bf16 v[36:51], v[180:183], v[188:191], v[36:51]
	ds_read_b128 v[176:179], v159
	ds_read_b128 v[168:171], v160 offset:16384
	s_waitcnt lgkmcnt(2)
	v_mfma_f32_32x32x16_bf16 v[20:35], v[164:167], v[184:187], v[20:35]
	ds_read_b128 v[172:175], v160 offset:20480
	v_mfma_f32_32x32x16_bf16 v[4:19], v[164:167], v[188:191], v[4:19]
	s_waitcnt lgkmcnt(1)
	v_mfma_f32_32x32x16_bf16 v[52:67], v[176:179], v[168:171], v[52:67]
	ds_read_b128 v[180:183], v159 offset:4096
	s_waitcnt lgkmcnt(1)
	v_mfma_f32_32x32x16_bf16 v[36:51], v[176:179], v[172:175], v[36:51]
	ds_read_b128 v[164:167], v161
	ds_read_b128 v[184:187], v162 offset:16384
	s_waitcnt lgkmcnt(2)
	v_mfma_f32_32x32x16_bf16 v[20:35], v[180:183], v[168:171], v[20:35]
	ds_read_b128 v[188:191], v162 offset:20480
	v_mfma_f32_32x32x16_bf16 v[4:19], v[180:183], v[172:175], v[4:19]
	s_waitcnt lgkmcnt(1)
	v_mfma_f32_32x32x16_bf16 v[52:67], v[164:167], v[184:187], v[52:67]
	ds_read_b128 v[176:179], v161 offset:4096
	s_waitcnt lgkmcnt(1)
	v_mfma_f32_32x32x16_bf16 v[36:51], v[164:167], v[188:191], v[36:51]
	s_waitcnt lgkmcnt(0)
	v_mfma_f32_32x32x16_bf16 v[20:35], v[176:179], v[184:187], v[20:35]
	v_mfma_f32_32x32x16_bf16 v[4:19], v[176:179], v[188:191], v[4:19]
	s_setprio 0
	s_cmpk_gt_u32 s28, 0x73f
	s_barrier
	ds_write_b128 v155, v[84:87]
	s_waitcnt vmcnt(3)
	ds_write_b128 v155, v[96:99] offset:16384
	ds_write_b128 v155, v[92:95] offset:4096
	s_waitcnt vmcnt(2)
	ds_write_b128 v155, v[108:111] offset:20480
	ds_write_b128 v155, v[116:119] offset:8192
	s_waitcnt vmcnt(1)
	ds_write_b128 v155, v[120:123] offset:24576
	ds_write_b128 v155, v[124:127] offset:12288
	s_waitcnt vmcnt(0)
	ds_write_b128 v155, v[128:131] offset:28672
	s_waitcnt lgkmcnt(0)
	s_barrier
	s_cbranch_scc1 .LBB0_517
	v_mov_b32_e32 v92, v0
	v_mov_b32_e32 v93, v0
	v_mov_b32_e32 v94, v0
	v_mov_b32_e32 v95, v0
	v_mov_b64_e32 v[84:85], v[92:93]
	v_mov_b64_e32 v[86:87], v[94:95]
	s_and_saveexec_b64 s[22:23], s[4:5]
	s_cbranch_execz .LBB0_531
	v_lshl_add_u64 v[2:3], v[140:141], 0, v[132:133]
	v_add_co_u32_e32 v2, vcc, 0x9dd8000, v2
	s_nop 1
	v_addc_co_u32_e32 v3, vcc, 0, v3, vcc
	global_load_dwordx4 v[84:87], v[2:3], off offset:2432

.LBB0_968:
	s_addk_i32 s26, 0x80
	s_setprio 1
	ds_read_b128 v[164:167], v154
	ds_read_b128 v[168:171], v156 offset:16384
	ds_read_b128 v[172:175], v156 offset:20480
	s_waitcnt lgkmcnt(1)
	v_mfma_f32_32x32x16_bf16 v[52:67], v[164:167], v[168:171], v[52:67]
	ds_read_b128 v[176:179], v154 offset:4096
	s_waitcnt lgkmcnt(1)
	v_mfma_f32_32x32x16_bf16 v[36:51], v[164:167], v[172:175], v[36:51]
	ds_read_b128 v[180:183], v157
	ds_read_b128 v[184:187], v158 offset:16384
	s_waitcnt lgkmcnt(2)
	v_mfma_f32_32x32x16_bf16 v[20:35], v[176:179], v[168:171], v[20:35]
	ds_read_b128 v[188:191], v158 offset:20480
	v_mfma_f32_32x32x16_bf16 v[4:19], v[176:179], v[172:175], v[4:19]
	s_waitcnt lgkmcnt(1)
	v_mfma_f32_32x32x16_bf16 v[52:67], v[180:183], v[184:187], v[52:67]
	ds_read_b128 v[164:167], v157 offset:4096
	s_waitcnt lgkmcnt(1)
	v_mfma_f32_32x32x16_bf16 v[36:51], v[180:183], v[188:191], v[36:51]
	ds_read_b128 v[176:179], v159
	ds_read_b128 v[168:171], v160 offset:16384
	s_waitcnt lgkmcnt(2)
	v_mfma_f32_32x32x16_bf16 v[20:35], v[164:167], v[184:187], v[20:35]
	ds_read_b128 v[172:175], v160 offset:20480
	v_mfma_f32_32x32x16_bf16 v[4:19], v[164:167], v[188:191], v[4:19]
	s_waitcnt lgkmcnt(1)
	v_mfma_f32_32x32x16_bf16 v[52:67], v[176:179], v[168:171], v[52:67]
	ds_read_b128 v[180:183], v159 offset:4096
	s_waitcnt lgkmcnt(1)
	v_mfma_f32_32x32x16_bf16 v[36:51], v[176:179], v[172:175], v[36:51]
	ds_read_b128 v[164:167], v161
	ds_read_b128 v[184:187], v162 offset:16384
	s_waitcnt lgkmcnt(2)
	v_mfma_f32_32x32x16_bf16 v[20:35], v[180:183], v[168:171], v[20:35]
	ds_read_b128 v[188:191], v162 offset:20480
	v_mfma_f32_32x32x16_bf16 v[4:19], v[180:183], v[172:175], v[4:19]
	s_waitcnt lgkmcnt(1)
	v_mfma_f32_32x32x16_bf16 v[52:67], v[164:167], v[184:187], v[52:67]
	ds_read_b128 v[176:179], v161 offset:4096
	s_waitcnt lgkmcnt(1)
	v_mfma_f32_32x32x16_bf16 v[36:51], v[164:167], v[188:191], v[36:51]
	s_waitcnt lgkmcnt(0)
	v_mfma_f32_32x32x16_bf16 v[20:35], v[176:179], v[184:187], v[20:35]
	v_mfma_f32_32x32x16_bf16 v[4:19], v[176:179], v[188:191], v[4:19]
	s_setprio 0
	v_lshl_add_u64 v[134:135], v[134:135], 0, s[82:83]
	v_lshl_add_u64 v[136:137], v[136:137], 0, s[82:83]
	v_lshl_add_u64 v[138:139], v[138:139], 0, s[82:83]
	v_lshl_add_u64 v[140:141], v[140:141], 0, s[82:83]
	v_lshl_add_u64 v[142:143], v[142:143], 0, s[82:83]
	v_lshl_add_u64 v[144:145], v[144:145], 0, s[82:83]
	v_lshl_add_u64 v[146:147], v[146:147], 0, s[82:83]
	s_andn2_b64 vcc, exec, s[2:3]
	v_lshl_add_u64 v[148:149], v[148:149], 0, s[82:83]
	s_barrier
	s_cbranch_vccz .LBB0_988

.LBB0_979:
	s_setprio 1
	ds_read_b128 v[164:167], v154
	ds_read_b128 v[168:171], v156 offset:16384
	ds_read_b128 v[172:175], v156 offset:20480
	s_waitcnt lgkmcnt(1)
	v_mfma_f32_32x32x16_bf16 v[52:67], v[164:167], v[168:171], v[52:67]
	ds_read_b128 v[176:179], v154 offset:4096
	s_waitcnt lgkmcnt(1)
	v_mfma_f32_32x32x16_bf16 v[36:51], v[164:167], v[172:175], v[36:51]
	ds_read_b128 v[180:183], v157
	ds_read_b128 v[184:187], v158 offset:16384
	s_waitcnt lgkmcnt(2)
	v_mfma_f32_32x32x16_bf16 v[20:35], v[176:179], v[168:171], v[20:35]
	ds_read_b128 v[188:191], v158 offset:20480
	v_mfma_f32_32x32x16_bf16 v[4:19], v[176:179], v[172:175], v[4:19]
	s_waitcnt lgkmcnt(1)
	v_mfma_f32_32x32x16_bf16 v[52:67], v[180:183], v[184:187], v[52:67]
	ds_read_b128 v[164:167], v157 offset:4096
	s_waitcnt lgkmcnt(1)
	v_mfma_f32_32x32x16_bf16 v[36:51], v[180:183], v[188:191], v[36:51]
	ds_read_b128 v[176:179], v159
	ds_read_b128 v[168:171], v160 offset:16384
	s_waitcnt lgkmcnt(2)
	v_mfma_f32_32x32x16_bf16 v[20:35], v[164:167], v[184:187], v[20:35]
	ds_read_b128 v[172:175], v160 offset:20480
	v_mfma_f32_32x32x16_bf16 v[4:19], v[164:167], v[188:191], v[4:19]
	s_waitcnt lgkmcnt(1)
	v_mfma_f32_32x32x16_bf16 v[52:67], v[176:179], v[168:171], v[52:67]
	ds_read_b128 v[180:183], v159 offset:4096
	s_waitcnt lgkmcnt(1)
	v_mfma_f32_32x32x16_bf16 v[36:51], v[176:179], v[172:175], v[36:51]
	ds_read_b128 v[164:167], v161
	ds_read_b128 v[184:187], v162 offset:16384
	s_waitcnt lgkmcnt(2)
	v_mfma_f32_32x32x16_bf16 v[20:35], v[180:183], v[168:171], v[20:35]
	ds_read_b128 v[188:191], v162 offset:20480
	v_mfma_f32_32x32x16_bf16 v[4:19], v[180:183], v[172:175], v[4:19]
	s_waitcnt lgkmcnt(1)
	v_mfma_f32_32x32x16_bf16 v[52:67], v[164:167], v[184:187], v[52:67]
	ds_read_b128 v[176:179], v161 offset:4096
	s_waitcnt lgkmcnt(1)
	v_mfma_f32_32x32x16_bf16 v[36:51], v[164:167], v[188:191], v[36:51]
	s_waitcnt lgkmcnt(0)
	v_mfma_f32_32x32x16_bf16 v[20:35], v[176:179], v[184:187], v[20:35]
	v_mfma_f32_32x32x16_bf16 v[4:19], v[176:179], v[188:191], v[4:19]
	s_setprio 0
	s_cmpk_gt_u32 s26, 0x73f
	s_barrier
	ds_write_b128 v155, v[88:91]
	s_waitcnt vmcnt(3)
	ds_write_b128 v155, v[100:103] offset:16384
	ds_write_b128 v155, v[92:95] offset:4096
	s_waitcnt vmcnt(2)
	ds_write_b128 v155, v[112:115] offset:20480
	ds_write_b128 v155, v[116:119] offset:8192
	s_waitcnt vmcnt(1)
	ds_write_b128 v155, v[120:123] offset:24576
	ds_write_b128 v155, v[124:127] offset:12288
	s_waitcnt vmcnt(0)
	ds_write_b128 v155, v[128:131] offset:28672
	s_waitcnt lgkmcnt(0)
	s_barrier
	s_cbranch_scc1 .LBB0_968
	v_mov_b32_e32 v92, v0
	v_mov_b32_e32 v93, v0
	v_mov_b32_e32 v94, v0
	v_mov_b32_e32 v95, v0
	v_mov_b64_e32 v[88:89], v[92:93]
	v_mov_b64_e32 v[90:91], v[94:95]
	s_and_saveexec_b64 s[4:5], s[6:7]
	s_cbranch_execz .LBB0_982
	v_lshl_add_u64 v[2:3], v[140:141], 0, v[132:133]
	v_add_co_u32_e32 v2, vcc, 0x9dd8000, v2
	s_nop 1
	v_addc_co_u32_e32 v3, vcc, 0, v3, vcc
	global_load_dwordx4 v[88:91], v[2:3], off offset:2432
